# sample-row split-K GEMMs: operand loads batched (9-step rolling window for K=2816; 12 loads per trip for K=1024) instead of load-wait-mfma per k-step
# speedup vs baseline: 1.0489x; 1.0059x over previous
; template <int MODE> __device__ __forceinline__ void small_gemm_res(LAS unsigned char* lds, const bf16* A, const bf16* Bt, int K, const float* base, const bf16* baseb, float* H, bf16* XN, float* SS, float alpha, const bf16* GGs, int bx, int G, int tid) {
;     ...
;         const bf16* ap = A + (size_t)(t0 + r32) * K + w * kw + 8 * hi;
;         const bf16* b0p = Bt + (size_t)(n0 + r32) * K + w * kw + 8 * hi; const bf16* b1p = b0p + (size_t)32 * K;
; #pragma unroll 4
;         for (int k = 0; k < kw; k += 16) {
;             const bf16x8 x = *(const bf16x8*)(ap + k), w0 = *(const bf16x8*)(b0p + k), w1 = *(const bf16x8*)(b1p + k);
;             acc0 = __builtin_amdgcn_mfma_f32_32x32x16_bf16(w0, x, acc0, 0, 0, 0); acc1 = __builtin_amdgcn_mfma_f32_32x32x16_bf16(w1, x, acc1, 0, 0, 0);
;         }
.LBB0_290:
	s_and_b32 s14, s1, 0x3c0
	v_or_b32_e32 v2, s14, v41
	v_mul_u32_u24_e32 v2, 0xb00, v2
	v_lshlrev_b32_e32 v34, 1, v2
	v_lshl_add_u64 v[86:87], v[38:39], 0, v[34:35]
	s_and_b32 s16, s3, 0xffffffe0
	v_or_b32_e32 v6, s16, v41
	v_mad_i64_i32 v[88:89], s[22:23], v6, s19, v[36:37]
	v_add_co_u32_e32 v90, vcc, 0x2c000, v86
	v_addc_co_u32_e32 v91, vcc, 0, v87, vcc
	global_load_dwordx4 v[72:75], v[86:87], off
	global_load_dwordx4 v[76:79], v[88:89], off
	global_load_dwordx4 v[80:83], v[90:91], off
	global_load_dwordx4 v[92:95], v[86:87], off offset:32
	global_load_dwordx4 v[96:99], v[88:89], off offset:32
	global_load_dwordx4 v[100:103], v[90:91], off offset:32
	global_load_dwordx4 v[104:107], v[86:87], off offset:64
	global_load_dwordx4 v[108:111], v[88:89], off offset:64
	global_load_dwordx4 v[112:115], v[90:91], off offset:64
	global_load_dwordx4 v[116:119], v[86:87], off offset:96
	global_load_dwordx4 v[120:123], v[88:89], off offset:96
	global_load_dwordx4 v[124:127], v[90:91], off offset:96
	global_load_dwordx4 v[208:211], v[86:87], off offset:128
	global_load_dwordx4 v[212:215], v[88:89], off offset:128
	global_load_dwordx4 v[216:219], v[90:91], off offset:128
	global_load_dwordx4 v[220:223], v[86:87], off offset:160
	global_load_dwordx4 v[224:227], v[88:89], off offset:160
	global_load_dwordx4 v[228:231], v[90:91], off offset:160
	global_load_dwordx4 v[232:235], v[86:87], off offset:192
	global_load_dwordx4 v[236:239], v[88:89], off offset:192
	global_load_dwordx4 v[166:169], v[90:91], off offset:192
	global_load_dwordx4 v[170:173], v[86:87], off offset:224
	global_load_dwordx4 v[174:177], v[88:89], off offset:224
	global_load_dwordx4 v[182:185], v[90:91], off offset:224
	global_load_dwordx4 v[186:189], v[86:87], off offset:256
	global_load_dwordx4 v[190:193], v[88:89], off offset:256
	global_load_dwordx4 v[240:243], v[90:91], off offset:256
	s_waitcnt vmcnt(24)
	v_mfma_f32_32x32x16_bf16 v[2:17], v[72:75], v[76:79], 0
	v_mfma_f32_32x32x16_bf16 v[18:33], v[80:83], v[76:79], 0
	global_load_dwordx4 v[72:75], v[86:87], off offset:288
	global_load_dwordx4 v[76:79], v[88:89], off offset:288
	global_load_dwordx4 v[80:83], v[90:91], off offset:288
	s_waitcnt vmcnt(24)
	v_mfma_f32_32x32x16_bf16 v[2:17], v[92:95], v[96:99], v[2:17]
	v_mfma_f32_32x32x16_bf16 v[18:33], v[100:103], v[96:99], v[18:33]
	global_load_dwordx4 v[92:95], v[86:87], off offset:320
	global_load_dwordx4 v[96:99], v[88:89], off offset:320
	global_load_dwordx4 v[100:103], v[90:91], off offset:320
	s_waitcnt vmcnt(24)
	v_mfma_f32_32x32x16_bf16 v[2:17], v[104:107], v[108:111], v[2:17]
	v_mfma_f32_32x32x16_bf16 v[18:33], v[112:115], v[108:111], v[18:33]
	global_load_dwordx4 v[104:107], v[86:87], off offset:352
	global_load_dwordx4 v[108:111], v[88:89], off offset:352
	global_load_dwordx4 v[112:115], v[90:91], off offset:352
	s_waitcnt vmcnt(24)
	v_mfma_f32_32x32x16_bf16 v[2:17], v[116:119], v[120:123], v[2:17]
	v_mfma_f32_32x32x16_bf16 v[18:33], v[124:127], v[120:123], v[18:33]
	global_load_dwordx4 v[116:119], v[86:87], off offset:384
	global_load_dwordx4 v[120:123], v[88:89], off offset:384
	global_load_dwordx4 v[124:127], v[90:91], off offset:384
	s_waitcnt vmcnt(24)
	v_mfma_f32_32x32x16_bf16 v[2:17], v[208:211], v[212:215], v[2:17]
	v_mfma_f32_32x32x16_bf16 v[18:33], v[216:219], v[212:215], v[18:33]
	global_load_dwordx4 v[208:211], v[86:87], off offset:416
	global_load_dwordx4 v[212:215], v[88:89], off offset:416
	global_load_dwordx4 v[216:219], v[90:91], off offset:416
	s_waitcnt vmcnt(24)
	v_mfma_f32_32x32x16_bf16 v[2:17], v[220:223], v[224:227], v[2:17]
	v_mfma_f32_32x32x16_bf16 v[18:33], v[228:231], v[224:227], v[18:33]
	global_load_dwordx4 v[220:223], v[86:87], off offset:448
	global_load_dwordx4 v[224:227], v[88:89], off offset:448
	global_load_dwordx4 v[228:231], v[90:91], off offset:448
	s_waitcnt vmcnt(24)
	v_mfma_f32_32x32x16_bf16 v[2:17], v[232:235], v[236:239], v[2:17]
	v_mfma_f32_32x32x16_bf16 v[18:33], v[166:169], v[236:239], v[18:33]
	global_load_dwordx4 v[232:235], v[86:87], off offset:480
	global_load_dwordx4 v[236:239], v[88:89], off offset:480
	global_load_dwordx4 v[166:169], v[90:91], off offset:480
	s_waitcnt vmcnt(24)
	v_mfma_f32_32x32x16_bf16 v[2:17], v[170:173], v[174:177], v[2:17]
	v_mfma_f32_32x32x16_bf16 v[18:33], v[182:185], v[174:177], v[18:33]
	global_load_dwordx4 v[170:173], v[86:87], off offset:512
	global_load_dwordx4 v[174:177], v[88:89], off offset:512
	global_load_dwordx4 v[182:185], v[90:91], off offset:512
	s_waitcnt vmcnt(24)
	v_mfma_f32_32x32x16_bf16 v[2:17], v[186:189], v[190:193], v[2:17]
	v_mfma_f32_32x32x16_bf16 v[18:33], v[240:243], v[190:193], v[18:33]
	global_load_dwordx4 v[186:189], v[86:87], off offset:544
	global_load_dwordx4 v[190:193], v[88:89], off offset:544
	global_load_dwordx4 v[240:243], v[90:91], off offset:544
	s_waitcnt vmcnt(24)
	v_mfma_f32_32x32x16_bf16 v[2:17], v[72:75], v[76:79], v[2:17]
	v_mfma_f32_32x32x16_bf16 v[18:33], v[80:83], v[76:79], v[18:33]
	global_load_dwordx4 v[72:75], v[86:87], off offset:576
	global_load_dwordx4 v[76:79], v[88:89], off offset:576
	global_load_dwordx4 v[80:83], v[90:91], off offset:576
	s_waitcnt vmcnt(24)
	v_mfma_f32_32x32x16_bf16 v[2:17], v[92:95], v[96:99], v[2:17]
	v_mfma_f32_32x32x16_bf16 v[18:33], v[100:103], v[96:99], v[18:33]
	global_load_dwordx4 v[92:95], v[86:87], off offset:608
	global_load_dwordx4 v[96:99], v[88:89], off offset:608
	global_load_dwordx4 v[100:103], v[90:91], off offset:608
	s_waitcnt vmcnt(24)
; #define LAS __attribute__((address_space(3)))
; __device__ __forceinline__ unsigned pk2(float lo, float hi) { return pg8::cvt_pk_bf16(lo, hi); }
; __device__ __forceinline__ float bflo(unsigned w) { return __uint_as_float(w << 16); }
; __device__ __forceinline__ float bfhi(unsigned w) { return __uint_as_float(w & 0xffff0000u); }
; __device__ __forceinline__ int crow(int r, int hi) { return (r & 3) + 8 * (r >> 2) + 4 * hi; }
; template <int MODE> __device__ __forceinline__ void small_gemm_res(LAS unsigned char* lds, const bf16* A, const bf16* Bt, int K, const float* base, const bf16* baseb, float* H, bf16* XN, float* SS, float alpha, const bf16* GGs, int bx, int G, int tid) {
;     ...
;         for (int k = 0; k < kw; k += 16) {
;             const bf16x8 x = *(const bf16x8*)(ap + k), w0 = *(const bf16x8*)(b0p + k), w1 = *(const bf16x8*)(b1p + k);
;             acc0 = __builtin_amdgcn_mfma_f32_32x32x16_bf16(w0, x, acc0, 0, 0, 0); acc1 = __builtin_amdgcn_mfma_f32_32x32x16_bf16(w1, x, acc1, 0, 0, 0);
;         }
;         LAS float* Pw = P + w * 2112;
; #pragma unroll
;         for (int r = 0; r < 16; ++r) { Pw[crow(r, hi) * 33 + r32] = acc0[r]; Pw[(32 + crow(r, hi)) * 33 + r32] = acc1[r]; }
;         __syncthreads();
;         const int tok = tid >> 4, nq = tid & 15;
;         float v[4] = {0.f, 0.f, 0.f, 0.f};
; #pragma unroll
;         for (int ww = 0; ww < 8; ++ww)
; #pragma unroll
;             for (int e = 0; e < 4; ++e) v[e] += P[ww * 2112 + (4 * nq + e) * 33 + tok];
;         const size_t off = (size_t)(t0 + tok) * 1024 + n0 + 4 * nq;
;         if (MODE == 0) {
;             f32x4 b; if (baseb) { const u32x2 bw = *(const u32x2*)(baseb + off); b = (f32x4){bflo(bw.x), bfhi(bw.x), bflo(bw.y), bfhi(bw.y)}; } else b = *(const f32x4*)(base + off);
;             const f32x4 hv = (f32x4){b[0] + alpha * v[0], b[1] + alpha * v[1], b[2] + alpha * v[2], b[3] + alpha * v[3]};
;             if (H) *(f32x4*)(H + off) = hv;
;             if (XN) { u32x2 xw; xw.x = pk2(hv[0], hv[1]); xw.y = pk2(hv[2], hv[3]); *(u32x2*)(XN + off) = xw; }
;             if (SS) { float ss = (hv[0] * hv[0] + hv[1] * hv[1]) + (hv[2] * hv[2] + hv[3] * hv[3]);
;                 ss += __shfl_xor(ss, 1); ss += __shfl_xor(ss, 2); ss += __shfl_xor(ss, 4); ss += __shfl_xor(ss, 8);
;                 if (nq == 0) SS[(size_t)(t0 + tok) * 16 + (n0 >> 6)] = ss; }
	v_mfma_f32_32x32x16_bf16 v[2:17], v[104:107], v[108:111], v[2:17]
	v_mfma_f32_32x32x16_bf16 v[18:33], v[112:115], v[108:111], v[18:33]
	global_load_dwordx4 v[104:107], v[86:87], off offset:640
	global_load_dwordx4 v[108:111], v[88:89], off offset:640
	global_load_dwordx4 v[112:115], v[90:91], off offset:640
	s_waitcnt vmcnt(24)
	v_mfma_f32_32x32x16_bf16 v[2:17], v[116:119], v[120:123], v[2:17]
	v_mfma_f32_32x32x16_bf16 v[18:33], v[124:127], v[120:123], v[18:33]
	global_load_dwordx4 v[116:119], v[86:87], off offset:672
	global_load_dwordx4 v[120:123], v[88:89], off offset:672
	global_load_dwordx4 v[124:127], v[90:91], off offset:672
	s_waitcnt vmcnt(24)
	v_mfma_f32_32x32x16_bf16 v[2:17], v[208:211], v[212:215], v[2:17]
	v_mfma_f32_32x32x16_bf16 v[18:33], v[216:219], v[212:215], v[18:33]
	s_waitcnt vmcnt(21)
	v_mfma_f32_32x32x16_bf16 v[2:17], v[220:223], v[224:227], v[2:17]
	v_mfma_f32_32x32x16_bf16 v[18:33], v[228:231], v[224:227], v[18:33]
	s_waitcnt vmcnt(18)
	v_mfma_f32_32x32x16_bf16 v[2:17], v[232:235], v[236:239], v[2:17]
	v_mfma_f32_32x32x16_bf16 v[18:33], v[166:169], v[236:239], v[18:33]
	s_waitcnt vmcnt(15)
	v_mfma_f32_32x32x16_bf16 v[2:17], v[170:173], v[174:177], v[2:17]
	v_mfma_f32_32x32x16_bf16 v[18:33], v[182:185], v[174:177], v[18:33]
	s_waitcnt vmcnt(12)
	v_mfma_f32_32x32x16_bf16 v[2:17], v[186:189], v[190:193], v[2:17]
	v_mfma_f32_32x32x16_bf16 v[18:33], v[240:243], v[190:193], v[18:33]
	s_waitcnt vmcnt(9)
	v_mfma_f32_32x32x16_bf16 v[2:17], v[72:75], v[76:79], v[2:17]
	v_mfma_f32_32x32x16_bf16 v[18:33], v[80:83], v[76:79], v[18:33]
	s_waitcnt vmcnt(6)
	v_mfma_f32_32x32x16_bf16 v[2:17], v[92:95], v[96:99], v[2:17]
	v_mfma_f32_32x32x16_bf16 v[18:33], v[100:103], v[96:99], v[18:33]
	s_waitcnt vmcnt(3)
	v_mfma_f32_32x32x16_bf16 v[2:17], v[104:107], v[108:111], v[2:17]
	v_mfma_f32_32x32x16_bf16 v[18:33], v[112:115], v[108:111], v[18:33]
	s_waitcnt vmcnt(0)
	v_mfma_f32_32x32x16_bf16 v[2:17], v[116:119], v[120:123], v[2:17]
	v_mfma_f32_32x32x16_bf16 v[18:33], v[124:127], v[120:123], v[18:33]
	s_nop 9
	ds_write2_b32 v43, v2, v3 offset1:33
	v_add_u32_e32 v2, s16, v42
	v_ashrrev_i32_e32 v3, 31, v2
	ds_write2_b32 v45, v18, v19 offset0:32 offset1:65
	ds_write2_b32 v43, v4, v5 offset0:66 offset1:99
	ds_write2_b32 v45, v20, v21 offset0:98 offset1:131
	ds_write2_b32 v46, v6, v7 offset0:8 offset1:41
	ds_write2_b32 v47, v22, v23 offset0:40 offset1:73
	ds_write2_b32 v46, v8, v9 offset0:74 offset1:107
	ds_write2_b32 v47, v24, v25 offset0:106 offset1:139
	ds_write2_b32 v48, v10, v11 offset0:16 offset1:49
	ds_write2_b32 v49, v26, v27 offset0:48 offset1:81
	ds_write2_b32 v48, v12, v13 offset0:82 offset1:115
	ds_write2_b32 v49, v28, v29 offset0:114 offset1:147
	ds_write2_b32 v50, v14, v15 offset0:24 offset1:57
	ds_write2_b32 v51, v30, v31 offset0:56 offset1:89
	ds_write2_b32 v50, v16, v17 offset0:90 offset1:123
	ds_write2_b32 v51, v32, v33 offset0:122 offset1:155
	v_lshlrev_b64 v[8:9], 10, v[2:3]
	v_or_b32_e32 v4, s14, v8
	v_or_b32_e32 v8, v4, v40
	s_waitcnt lgkmcnt(0)
	v_lshl_add_u64 v[4:5], v[8:9], 2, s[6:7]
	s_barrier
	global_load_dwordx4 v[4:7], v[4:5], off
	ds_read2_b32 v[10:11], v44 offset1:33
	ds_read2_b32 v[12:13], v44 offset0:66 offset1:99
	ds_read2_b32 v[14:15], v52 offset0:64 offset1:97
	ds_read2_b32 v[16:17], v52 offset0:130 offset1:163
	ds_read2_b32 v[18:19], v53 offset0:128 offset1:161
	ds_read2_b32 v[20:21], v53 offset0:194 offset1:227
	ds_read2_b32 v[22:23], v54 offset0:192 offset1:225
	ds_read2_b32 v[24:25], v55 offset0:2 offset1:35
	ds_read2_b32 v[26:27], v56 offset1:33
	ds_read2_b32 v[28:29], v56 offset0:66 offset1:99
	ds_read2_b32 v[30:31], v57 offset0:64 offset1:97
	ds_read2_b32 v[32:33], v57 offset0:130 offset1:163
	ds_read2_b32 v[62:63], v58 offset0:128 offset1:161
	ds_read2_b32 v[64:65], v58 offset0:194 offset1:227
	ds_read2_b32 v[66:67], v59 offset0:192 offset1:225
	ds_read2_b32 v[68:69], v60 offset0:2 offset1:35
	s_waitcnt lgkmcnt(14)
	v_pk_add_f32 v[10:11], v[10:11], 0 op_sel_hi:[1,0]
	s_waitcnt lgkmcnt(13)
	v_pk_add_f32 v[10:11], v[10:11], v[14:15]
	s_waitcnt lgkmcnt(11)
	v_pk_add_f32 v[10:11], v[10:11], v[18:19]
	s_waitcnt lgkmcnt(9)
	v_pk_add_f32 v[10:11], v[10:11], v[22:23]
	s_waitcnt lgkmcnt(7)
	v_pk_add_f32 v[10:11], v[10:11], v[26:27]
	s_waitcnt lgkmcnt(5)
	v_pk_add_f32 v[10:11], v[10:11], v[30:31]
	s_waitcnt lgkmcnt(3)
	v_pk_add_f32 v[10:11], v[10:11], v[62:63]
	s_waitcnt lgkmcnt(1)
	v_pk_add_f32 v[10:11], v[10:11], v[66:67]
	s_waitcnt vmcnt(0)
	v_pk_fma_f32 v[10:11], v[10:11], 0.5, v[4:5] op_sel_hi:[1,0,1]
	v_pk_add_f32 v[4:5], v[12:13], 0 op_sel_hi:[1,0]
	s_nop 0
	v_pk_add_f32 v[4:5], v[4:5], v[16:17]
	s_nop 0
	v_pk_add_f32 v[4:5], v[4:5], v[20:21]
	s_nop 0
	v_pk_add_f32 v[4:5], v[4:5], v[24:25]
	s_nop 0
	v_pk_add_f32 v[4:5], v[4:5], v[28:29]
	s_nop 0
	v_pk_add_f32 v[4:5], v[4:5], v[32:33]
	s_nop 0
	v_pk_add_f32 v[4:5], v[4:5], v[64:65]
	s_waitcnt lgkmcnt(0)
	v_pk_add_f32 v[4:5], v[4:5], v[68:69]
	s_nop 0
	v_pk_fma_f32 v[6:7], v[4:5], 0.5, v[6:7] op_sel_hi:[1,0,1]
	v_pk_mul_f32 v[4:5], v[10:11], v[10:11]
	v_pk_mul_f32 v[12:13], v[6:7], v[6:7]
	v_add_f32_e32 v4, v4, v5
	v_add_f32_e32 v12, v12, v13
	v_add_f32_e32 v4, v4, v12
	ds_bpermute_b32 v5, v181, v4
	v_cvt_pk_bf16_f32 v10, v10, v11
	v_cvt_pk_bf16_f32 v11, v6, v7
	v_lshl_add_u64 v[6:7], v[8:9], 1, s[10:11]
	global_store_dwordx2 v[6:7], v[10:11], off
	s_waitcnt lgkmcnt(0)
	v_add_f32_e32 v4, v4, v5
	ds_bpermute_b32 v5, v196, v4
	s_waitcnt lgkmcnt(0)
	v_add_f32_e32 v4, v4, v5
	ds_bpermute_b32 v5, v197, v4
	s_waitcnt lgkmcnt(0)
	v_add_f32_e32 v4, v4, v5
	ds_bpermute_b32 v5, v198, v4
	s_and_saveexec_b64 s[16:17], s[8:9]
	s_cbranch_execz .LBB0_289
	v_lshlrev_b64 v[2:3], 6, v[2:3]
	v_lshl_add_u64 v[2:3], s[12:13], 0, v[2:3]
	s_lshr_b32 s14, s14, 4
	s_waitcnt lgkmcnt(0)
	v_add_f32_e32 v4, v4, v5
	v_lshl_add_u64 v[2:3], v[2:3], 0, s[14:15]
	global_store_dword v[2:3], v4, off
	s_branch .LBB0_289

; #define LAS __attribute__((address_space(3)))
; __device__ __forceinline__ unsigned pk2(float lo, float hi) { return pg8::cvt_pk_bf16(lo, hi); }
; template <int MODE> __device__ __forceinline__ void small_gemm_res(LAS unsigned char* lds, const bf16* A, const bf16* Bt, int K, const float* base, const bf16* baseb, float* H, bf16* XN, float* SS, float alpha, const bf16* GGs, int bx, int G, int tid) {
;     ...
;         const bf16* ap = A + (size_t)(t0 + r32) * K + w * kw + 8 * hi;
;         const bf16* b0p = Bt + (size_t)(n0 + r32) * K + w * kw + 8 * hi; const bf16* b1p = b0p + (size_t)32 * K;
; #pragma unroll 4
;         for (int k = 0; k < kw; k += 16) {
;             const bf16x8 x = *(const bf16x8*)(ap + k), w0 = *(const bf16x8*)(b0p + k), w1 = *(const bf16x8*)(b1p + k);
;             acc0 = __builtin_amdgcn_mfma_f32_32x32x16_bf16(w0, x, acc0, 0, 0, 0); acc1 = __builtin_amdgcn_mfma_f32_32x32x16_bf16(w1, x, acc1, 0, 0, 0);
;         }
;         LAS float* Pw = P + w * 2112;
; #pragma unroll
;         for (int r = 0; r < 16; ++r) { Pw[crow(r, hi) * 33 + r32] = acc0[r]; Pw[(32 + crow(r, hi)) * 33 + r32] = acc1[r]; }
;         __syncthreads();
;         const int tok = tid >> 4, nq = tid & 15;
;         float v[4] = {0.f, 0.f, 0.f, 0.f};
; #pragma unroll
;         for (int ww = 0; ww < 8; ++ww)
; #pragma unroll
;             for (int e = 0; e < 4; ++e) v[e] += P[ww * 2112 + (4 * nq + e) * 33 + tok];
;         const size_t off = (size_t)(t0 + tok) * 1024 + n0 + 4 * nq;
;         if (MODE == 0) {
;             f32x4 b; if (baseb) { const u32x2 bw = *(const u32x2*)(baseb + off); b = (f32x4){bflo(bw.x), bfhi(bw.x), bflo(bw.y), bfhi(bw.y)}; } else b = *(const f32x4*)(base + off);
;             const f32x4 hv = (f32x4){b[0] + alpha * v[0], b[1] + alpha * v[1], b[2] + alpha * v[2], b[3] + alpha * v[3]};
;             if (H) *(f32x4*)(H + off) = hv;
;             if (XN) { u32x2 xw; xw.x = pk2(hv[0], hv[1]); xw.y = pk2(hv[2], hv[3]); *(u32x2*)(XN + off) = xw; }
;             if (SS) { float ss = (hv[0] * hv[0] + hv[1] * hv[1]) + (hv[2] * hv[2] + hv[3] * hv[3]);
;                 ss += __shfl_xor(ss, 1); ss += __shfl_xor(ss, 2); ss += __shfl_xor(ss, 4); ss += __shfl_xor(ss, 8);
;                 if (nq == 0) SS[(size_t)(t0 + tok) * 16 + (n0 >> 6)] = ss; }
;         } else {
;             const u32x2 gw = *(const u32x2*)(GGs + (size_t)(t0 + tok) * 2048 + n0 + 4 * nq);
.LBB0_775:
	v_lshl_add_u64 v[58:59], v[42:43], 0, v[2:3]
	s_mov_b32 s20, 0x2100000
	v_add_co_u32_e32 v64, vcc, s20, v58
	s_mov_b32 s20, 0x2110000
	s_nop 0
	v_addc_co_u32_e32 v65, vcc, 0, v59, vcc
	v_add_co_u32_e32 v66, vcc, s20, v58
	v_lshl_add_u64 v[62:63], v[42:43], 0, v[40:41]
	s_nop 0
	v_addc_co_u32_e32 v67, vcc, 0, v59, vcc
	s_add_i32 s7, s7, 64
	v_lshl_add_u64 v[42:43], v[42:43], 0, s[76:77]
	s_cmpk_gt_u32 s7, 0x6f
	global_load_dwordx4 v[68:71], v[62:63], off offset:-64
	global_load_dwordx4 v[72:75], v[64:65], off
	global_load_dwordx4 v[76:79], v[66:67], off
	global_load_dwordx4 v[80:83], v[62:63], off offset:-32
	global_load_dwordx4 v[92:95], v[64:65], off offset:32
	global_load_dwordx4 v[96:99], v[66:67], off offset:32
	global_load_dwordx4 v[100:103], v[62:63], off
	global_load_dwordx4 v[104:107], v[64:65], off offset:64
	global_load_dwordx4 v[108:111], v[66:67], off offset:64
	global_load_dwordx4 v[112:115], v[62:63], off offset:32
	global_load_dwordx4 v[116:119], v[64:65], off offset:96
	global_load_dwordx4 v[120:123], v[66:67], off offset:96
	s_waitcnt vmcnt(9)
	v_mfma_f32_32x32x16_bf16 v[4:19], v[72:75], v[68:71], v[4:19]
	v_mfma_f32_32x32x16_bf16 v[20:35], v[76:79], v[68:71], v[20:35]
	s_waitcnt vmcnt(6)
	v_mfma_f32_32x32x16_bf16 v[4:19], v[92:95], v[80:83], v[4:19]
	v_mfma_f32_32x32x16_bf16 v[20:35], v[96:99], v[80:83], v[20:35]
	s_waitcnt vmcnt(3)
	v_mfma_f32_32x32x16_bf16 v[4:19], v[104:107], v[100:103], v[4:19]
	v_mfma_f32_32x32x16_bf16 v[20:35], v[108:111], v[100:103], v[20:35]
	s_waitcnt vmcnt(0)
	v_mfma_f32_32x32x16_bf16 v[4:19], v[116:119], v[112:115], v[4:19]
	v_mfma_f32_32x32x16_bf16 v[20:35], v[120:123], v[112:115], v[20:35]
	s_cbranch_scc0 .LBB0_775
	v_add_u32_e32 v2, 0x1000, v46
	s_nop 7
	ds_write2_b32 v46, v4, v5 offset1:33
	s_nop 0
	ds_write2_b32 v2, v20, v21 offset0:32 offset1:65
	ds_write2_b32 v46, v6, v7 offset0:66 offset1:99
	ds_write2_b32 v2, v22, v23 offset0:98 offset1:131
	v_add_u32_e32 v2, 0x400, v46
	v_add_u32_e32 v4, 0x1400, v46
	s_lshl_b32 s7, s6, 1
	ds_write2_b32 v2, v8, v9 offset0:8 offset1:41
	ds_write2_b32 v4, v24, v25 offset0:40 offset1:73
	ds_write2_b32 v2, v10, v11 offset0:74 offset1:107
	ds_write2_b32 v4, v26, v27 offset0:106 offset1:139
	v_add_u32_e32 v2, 0x800, v46
	v_add_u32_e32 v4, 0x1800, v46
	s_andn2_b32 s7, s7, 31
	ds_write2_b32 v2, v12, v13 offset0:16 offset1:49
	ds_write2_b32 v4, v28, v29 offset0:48 offset1:81
	ds_write2_b32 v2, v14, v15 offset0:82 offset1:115
	ds_write2_b32 v4, v30, v31 offset0:114 offset1:147
	v_add_u32_e32 v2, 0xc00, v46
	v_add_u32_e32 v4, 0x1c00, v46
	ds_write2_b32 v2, v16, v17 offset0:24 offset1:57
	ds_write2_b32 v4, v32, v33 offset0:56 offset1:89
	ds_write2_b32 v2, v18, v19 offset0:90 offset1:123
	ds_write2_b32 v4, v34, v35 offset0:122 offset1:155
	v_add_u32_e32 v4, s7, v45
	v_ashrrev_i32_e32 v5, 31, v4
	v_lshlrev_b64 v[6:7], 12, v[4:5]
	s_lshl_b32 s7, s6, 7
	v_lshl_add_u64 v[6:7], s[10:11], 0, v[6:7]
	s_and_b32 s78, s7, 0x780
	v_lshl_add_u64 v[6:7], v[6:7], 0, s[78:79]
	v_mov_b32_e32 v39, v3
	v_lshl_add_u64 v[6:7], v[6:7], 0, v[38:39]
	s_waitcnt lgkmcnt(0)
	s_barrier
	global_load_dwordx2 v[6:7], v[6:7], off
	v_add_u32_e32 v18, 0x4000, v48
	v_add_u32_e32 v20, 0x6000, v48
	v_add_u32_e32 v22, 0x6400, v48
	v_add_u32_e32 v26, 0x8400, v48
	v_add_u32_e32 v30, 0xa400, v48
	v_add_u32_e32 v34, 0xc400, v48
	v_add_u32_e32 v40, 0xe400, v48
	v_add_u32_e32 v42, 0xe800, v48
	v_add_u32_e32 v2, 0x2000, v48
	ds_read2_b32 v[8:9], v48 offset1:33
	ds_read2_b32 v[10:11], v48 offset0:66 offset1:99
	ds_read2_b32 v[12:13], v2 offset0:64 offset1:97
	ds_read2_b32 v[14:15], v2 offset0:130 offset1:163
	ds_read2_b32 v[16:17], v18 offset0:128 offset1:161
	ds_read2_b32 v[18:19], v18 offset0:194 offset1:227
	ds_read2_b32 v[20:21], v20 offset0:192 offset1:225
	ds_read2_b32 v[22:23], v22 offset0:2 offset1:35
	ds_read2_b32 v[24:25], v26 offset1:33
	ds_read2_b32 v[26:27], v26 offset0:66 offset1:99
	ds_read2_b32 v[28:29], v30 offset0:64 offset1:97
	ds_read2_b32 v[30:31], v30 offset0:130 offset1:163
	ds_read2_b32 v[32:33], v34 offset0:128 offset1:161
	ds_read2_b32 v[34:35], v34 offset0:194 offset1:227
	ds_read2_b32 v[40:41], v40 offset0:192 offset1:225
	ds_read2_b32 v[42:43], v42 offset0:2 offset1:35
	s_waitcnt lgkmcnt(14)
	v_pk_add_f32 v[8:9], v[8:9], 0 op_sel_hi:[1,0]
	v_pk_add_f32 v[10:11], v[10:11], 0 op_sel_hi:[1,0]
	s_waitcnt lgkmcnt(13)
	v_pk_add_f32 v[8:9], v[8:9], v[12:13]
	s_waitcnt lgkmcnt(12)
	v_pk_add_f32 v[10:11], v[10:11], v[14:15]
	s_waitcnt lgkmcnt(11)
	v_pk_add_f32 v[8:9], v[8:9], v[16:17]
	s_waitcnt lgkmcnt(10)
	v_pk_add_f32 v[10:11], v[10:11], v[18:19]
	s_waitcnt lgkmcnt(9)
	v_pk_add_f32 v[8:9], v[8:9], v[20:21]
	s_waitcnt lgkmcnt(8)
	v_pk_add_f32 v[10:11], v[10:11], v[22:23]
	s_waitcnt lgkmcnt(7)
	v_pk_add_f32 v[8:9], v[8:9], v[24:25]
	s_waitcnt lgkmcnt(6)
	v_pk_add_f32 v[10:11], v[10:11], v[26:27]
	s_waitcnt lgkmcnt(5)
	v_pk_add_f32 v[8:9], v[8:9], v[28:29]
	s_waitcnt lgkmcnt(4)
	v_pk_add_f32 v[10:11], v[10:11], v[30:31]
	s_waitcnt lgkmcnt(3)
	v_pk_add_f32 v[8:9], v[8:9], v[32:33]
	s_waitcnt lgkmcnt(2)
	v_pk_add_f32 v[10:11], v[10:11], v[34:35]
	v_lshlrev_b64 v[4:5], 11, v[4:5]
	v_readlane_b32 s0, v251, 44
	s_waitcnt lgkmcnt(1)
	v_pk_add_f32 v[8:9], v[8:9], v[40:41]
	s_waitcnt lgkmcnt(0)
	v_pk_add_f32 v[10:11], v[10:11], v[42:43]
	v_lshl_add_u64 v[4:5], s[4:5], 0, v[4:5]
	s_add_i32 s3, s3, s0
	v_readlane_b32 s0, v251, 48
	v_lshl_add_u64 v[4:5], v[4:5], 0, s[78:79]
	s_add_i32 s6, s6, s70
	s_add_i32 s2, s2, s0
	v_lshl_add_u64 v[4:5], v[4:5], 0, v[38:39]
	s_cmpk_gt_i32 s6, 0xff
	s_waitcnt vmcnt(0)
	v_lshlrev_b32_e32 v2, 16, v6
	v_and_b32_e32 v6, 0xffff0000, v6
	v_lshlrev_b32_e32 v12, 16, v7
	v_and_b32_e32 v7, 0xffff0000, v7
	v_mul_f32_e32 v2, 0xbfb8aa3b, v2
	v_mul_f32_e32 v6, 0xbfb8aa3b, v6
	v_mul_f32_e32 v12, 0xbfb8aa3b, v12
	v_mul_f32_e32 v7, 0xbfb8aa3b, v7
	v_exp_f32_e32 v2, v2
	v_exp_f32_e32 v6, v6
	v_exp_f32_e32 v12, v12
	v_exp_f32_e32 v7, v7
	v_add_f32_e32 v2, 1.0, v2
	v_add_f32_e32 v13, 1.0, v6
	v_add_f32_e32 v12, 1.0, v12
	v_add_f32_e32 v14, 1.0, v7
	v_rcp_f32_e32 v6, v2
	v_rcp_f32_e32 v7, v13
	v_rcp_f32_e32 v12, v12
	v_rcp_f32_e32 v13, v14
	v_pk_mul_f32 v[6:7], v[8:9], v[6:7]
	s_nop 0
	v_cvt_pk_bf16_f32 v6, v6, v7
	v_pk_mul_f32 v[8:9], v[10:11], v[12:13]
	s_nop 0
	v_cvt_pk_bf16_f32 v7, v8, v9
	global_store_dwordx2 v[4:5], v[6:7], off
	s_barrier
	s_cbranch_scc0 .LBB0_774

; #define LAS __attribute__((address_space(3)))
; template <int MODE> __device__ __forceinline__ void small_gemm_res(LAS unsigned char* lds, const bf16* A, const bf16* Bt, int K, const float* base, const bf16* baseb, float* H, bf16* XN, float* SS, float alpha, const bf16* GGs, int bx, int G, int tid) {
;     ...
;         for (int k = 0; k < kw; k += 16) {
;             const bf16x8 x = *(const bf16x8*)(ap + k), w0 = *(const bf16x8*)(b0p + k), w1 = *(const bf16x8*)(b1p + k);
;             acc0 = __builtin_amdgcn_mfma_f32_32x32x16_bf16(w0, x, acc0, 0, 0, 0); acc1 = __builtin_amdgcn_mfma_f32_32x32x16_bf16(w1, x, acc1, 0, 0, 0);
;         }
;         LAS float* Pw = P + w * 2112;
; #pragma unroll
;         for (int r = 0; r < 16; ++r) { Pw[crow(r, hi) * 33 + r32] = acc0[r]; Pw[(32 + crow(r, hi)) * 33 + r32] = acc1[r]; }
;         __syncthreads();
;         const int tok = tid >> 4, nq = tid & 15;
;         float v[4] = {0.f, 0.f, 0.f, 0.f};
; #pragma unroll
;         for (int ww = 0; ww < 8; ++ww)
; #pragma unroll
;             for (int e = 0; e < 4; ++e) v[e] += P[ww * 2112 + (4 * nq + e) * 33 + tok];
;         const size_t off = (size_t)(t0 + tok) * 1024 + n0 + 4 * nq;
;         if (MODE == 0) {
;             f32x4 b; if (baseb) { const u32x2 bw = *(const u32x2*)(baseb + off); b = (f32x4){bflo(bw.x), bfhi(bw.x), bflo(bw.y), bfhi(bw.y)}; } else b = *(const f32x4*)(base + off);
;             const f32x4 hv = (f32x4){b[0] + alpha * v[0], b[1] + alpha * v[1], b[2] + alpha * v[2], b[3] + alpha * v[3]};
;             if (H) *(f32x4*)(H + off) = hv;
;             if (XN) { u32x2 xw; xw.x = pk2(hv[0], hv[1]); xw.y = pk2(hv[2], hv[3]); *(u32x2*)(XN + off) = xw; }
;             if (SS) { float ss = (hv[0] * hv[0] + hv[1] * hv[1]) + (hv[2] * hv[2] + hv[3] * hv[3]);
;                 ss += __shfl_xor(ss, 1); ss += __shfl_xor(ss, 2); ss += __shfl_xor(ss, 4); ss += __shfl_xor(ss, 8);
;                 if (nq == 0) SS[(size_t)(t0 + tok) * 16 + (n0 >> 6)] = ss; }
;         } else {
;             const u32x2 gw = *(const u32x2*)(GGs + (size_t)(t0 + tok) * 2048 + n0 + 4 * nq);
;             f32x4 o = (f32x4){pg8::fast_sigmoid(bflo(gw.x)) * v[0], pg8::fast_sigmoid(bfhi(gw.x)) * v[1], pg8::fast_sigmoid(bflo(gw.y)) * v[2], pg8::fast_sigmoid(bfhi(gw.y)) * v[3]};
;             if (MODE == 1) { u32x2 xw; xw.x = pk2(o[0], o[1]); xw.y = pk2(o[2], o[3]); *(u32x2*)(XN + off) = xw; }
.LBB0_801:
	v_lshl_add_u64 v[56:57], v[42:43], 0, v[2:3]
	s_mov_b32 s14, 0x2300000
	v_add_co_u32_e32 v62, vcc, s14, v56
	s_mov_b32 s14, 0x2310000
	s_nop 0
	v_addc_co_u32_e32 v63, vcc, 0, v57, vcc
	v_add_co_u32_e32 v64, vcc, s14, v56
	v_lshl_add_u64 v[60:61], v[42:43], 0, v[40:41]
	s_nop 0
	v_addc_co_u32_e32 v65, vcc, 0, v57, vcc
	s_add_i32 s7, s7, 64
	v_lshl_add_u64 v[42:43], v[42:43], 0, s[76:77]
	s_cmpk_gt_u32 s7, 0x6f
	global_load_dwordx4 v[68:71], v[60:61], off offset:-64
	global_load_dwordx4 v[72:75], v[62:63], off
	global_load_dwordx4 v[76:79], v[64:65], off
	global_load_dwordx4 v[80:83], v[60:61], off offset:-32
	global_load_dwordx4 v[92:95], v[62:63], off offset:32
	global_load_dwordx4 v[96:99], v[64:65], off offset:32
	global_load_dwordx4 v[100:103], v[60:61], off
	global_load_dwordx4 v[104:107], v[62:63], off offset:64
	global_load_dwordx4 v[108:111], v[64:65], off offset:64
	global_load_dwordx4 v[112:115], v[60:61], off offset:32
	global_load_dwordx4 v[116:119], v[62:63], off offset:96
	global_load_dwordx4 v[120:123], v[64:65], off offset:96
	s_waitcnt vmcnt(9)
	v_mfma_f32_32x32x16_bf16 v[4:19], v[72:75], v[68:71], v[4:19]
	v_mfma_f32_32x32x16_bf16 v[20:35], v[76:79], v[68:71], v[20:35]
	s_waitcnt vmcnt(6)
	v_mfma_f32_32x32x16_bf16 v[4:19], v[92:95], v[80:83], v[4:19]
	v_mfma_f32_32x32x16_bf16 v[20:35], v[96:99], v[80:83], v[20:35]
	s_waitcnt vmcnt(3)
	v_mfma_f32_32x32x16_bf16 v[4:19], v[104:107], v[100:103], v[4:19]
	v_mfma_f32_32x32x16_bf16 v[20:35], v[108:111], v[100:103], v[20:35]
	s_waitcnt vmcnt(0)
	v_mfma_f32_32x32x16_bf16 v[4:19], v[116:119], v[112:115], v[4:19]
	v_mfma_f32_32x32x16_bf16 v[20:35], v[120:123], v[112:115], v[20:35]
	s_cbranch_scc0 .LBB0_801
	v_add_u32_e32 v2, 0x1000, v45
	s_nop 7
	ds_write2_b32 v45, v4, v5 offset1:33
	s_nop 0
	ds_write2_b32 v2, v20, v21 offset0:32 offset1:65
	ds_write2_b32 v45, v6, v7 offset0:66 offset1:99
	ds_write2_b32 v2, v22, v23 offset0:98 offset1:131
	v_add_u32_e32 v2, 0x400, v45
	v_add_u32_e32 v4, 0x1400, v45
	s_lshl_b32 s7, s6, 1
	ds_write2_b32 v2, v8, v9 offset0:8 offset1:41
	ds_write2_b32 v4, v24, v25 offset0:40 offset1:73
	ds_write2_b32 v2, v10, v11 offset0:74 offset1:107
	ds_write2_b32 v4, v26, v27 offset0:106 offset1:139
	v_add_u32_e32 v2, 0x800, v45
	v_add_u32_e32 v4, 0x1800, v45
	s_andn2_b32 s7, s7, 31
	ds_write2_b32 v2, v12, v13 offset0:16 offset1:49
	ds_write2_b32 v4, v28, v29 offset0:48 offset1:81
	ds_write2_b32 v2, v14, v15 offset0:82 offset1:115
	ds_write2_b32 v4, v30, v31 offset0:114 offset1:147
	v_add_u32_e32 v2, 0xc00, v45
	v_add_u32_e32 v4, 0x1c00, v45
	ds_write2_b32 v2, v16, v17 offset0:24 offset1:57
	ds_write2_b32 v4, v32, v33 offset0:56 offset1:89
	ds_write2_b32 v2, v18, v19 offset0:90 offset1:123
	ds_write2_b32 v4, v34, v35 offset0:122 offset1:155
	v_add_u32_e32 v4, s7, v44
	s_lshl_b32 s14, s6, 6
	v_ashrrev_i32_e32 v5, 31, v4
	s_and_b32 s14, s14, 0x3c0
	v_lshlrev_b64 v[6:7], 12, v[4:5]
	v_lshl_add_u64 v[6:7], s[18:19], 0, v[6:7]
	s_lshl_b32 s78, s14, 1
	v_lshl_add_u64 v[6:7], v[6:7], 0, s[78:79]
	v_lshlrev_b32_e32 v2, 1, v36
	v_lshl_add_u64 v[6:7], v[6:7], 0, v[2:3]
	s_waitcnt lgkmcnt(0)
	s_barrier
	global_load_dwordx2 v[6:7], v[6:7], off
	v_lshlrev_b64 v[4:5], 10, v[4:5]
	v_or_b32_e32 v2, s14, v4
	v_or_b32_e32 v4, v2, v36
	v_lshlrev_b64 v[4:5], 1, v[4:5]
	v_lshl_add_u64 v[8:9], s[4:5], 0, v[4:5]
	global_load_dwordx2 v[8:9], v[8:9], off
	v_add_u32_e32 v20, 0x4000, v47
	v_add_u32_e32 v22, 0x6000, v47
	v_add_u32_e32 v24, 0x6400, v47
	v_add_u32_e32 v28, 0x8400, v47
	v_add_u32_e32 v32, 0xa400, v47
	v_add_u32_e32 v40, 0xc400, v47
	v_add_u32_e32 v42, 0xe400, v47
	v_add_u32_e32 v48, 0xe800, v47
	v_add_u32_e32 v2, 0x2000, v47
	ds_read2_b32 v[10:11], v47 offset1:33
	ds_read2_b32 v[12:13], v47 offset0:66 offset1:99
	ds_read2_b32 v[14:15], v2 offset0:64 offset1:97
	ds_read2_b32 v[16:17], v2 offset0:130 offset1:163
	ds_read2_b32 v[18:19], v20 offset0:128 offset1:161
	ds_read2_b32 v[20:21], v20 offset0:194 offset1:227
	ds_read2_b32 v[22:23], v22 offset0:192 offset1:225
	ds_read2_b32 v[24:25], v24 offset0:2 offset1:35
	ds_read2_b32 v[26:27], v28 offset1:33
	ds_read2_b32 v[28:29], v28 offset0:66 offset1:99
	ds_read2_b32 v[30:31], v32 offset0:64 offset1:97
	ds_read2_b32 v[32:33], v32 offset0:130 offset1:163
	ds_read2_b32 v[34:35], v40 offset0:128 offset1:161
	ds_read2_b32 v[40:41], v40 offset0:194 offset1:227
	ds_read2_b32 v[42:43], v42 offset0:192 offset1:225
	ds_read2_b32 v[48:49], v48 offset0:2 offset1:35
	s_waitcnt lgkmcnt(14)
	v_pk_add_f32 v[10:11], v[10:11], 0 op_sel_hi:[1,0]
	v_pk_add_f32 v[12:13], v[12:13], 0 op_sel_hi:[1,0]
	s_waitcnt lgkmcnt(13)
	v_pk_add_f32 v[10:11], v[10:11], v[14:15]
	s_waitcnt lgkmcnt(12)
	v_pk_add_f32 v[12:13], v[12:13], v[16:17]
	s_waitcnt lgkmcnt(11)
	v_pk_add_f32 v[10:11], v[10:11], v[18:19]
	s_waitcnt lgkmcnt(10)
	v_pk_add_f32 v[12:13], v[12:13], v[20:21]
	s_waitcnt lgkmcnt(9)
	v_pk_add_f32 v[10:11], v[10:11], v[22:23]
	s_waitcnt lgkmcnt(8)
	v_pk_add_f32 v[12:13], v[12:13], v[24:25]
	s_waitcnt lgkmcnt(7)
	v_pk_add_f32 v[10:11], v[10:11], v[26:27]
	s_waitcnt lgkmcnt(6)
	v_pk_add_f32 v[12:13], v[12:13], v[28:29]
	s_waitcnt lgkmcnt(5)
	v_pk_add_f32 v[10:11], v[10:11], v[30:31]
	s_waitcnt lgkmcnt(4)
	v_pk_add_f32 v[12:13], v[12:13], v[32:33]
	s_waitcnt lgkmcnt(3)
	v_pk_add_f32 v[10:11], v[10:11], v[34:35]
	s_waitcnt lgkmcnt(2)
	v_pk_add_f32 v[12:13], v[12:13], v[40:41]
	v_readlane_b32 s0, v251, 44
	s_waitcnt lgkmcnt(1)
	v_pk_add_f32 v[10:11], v[10:11], v[42:43]
	s_waitcnt lgkmcnt(0)
	v_pk_add_f32 v[12:13], v[12:13], v[48:49]
	s_add_i32 s3, s3, s0
	v_readlane_b32 s0, v251, 48
	s_add_i32 s6, s6, s70
	s_add_i32 s2, s2, s0
	v_lshl_add_u64 v[4:5], s[16:17], 0, v[4:5]
	s_cmpk_gt_i32 s6, 0xff
	s_waitcnt vmcnt(1)
	v_lshlrev_b32_e32 v2, 16, v6
	v_and_b32_e32 v6, 0xffff0000, v6
	v_lshlrev_b32_e32 v14, 16, v7
	v_and_b32_e32 v7, 0xffff0000, v7
	v_mul_f32_e32 v2, 0xbfb8aa3b, v2
	v_mul_f32_e32 v6, 0xbfb8aa3b, v6
	v_mul_f32_e32 v14, 0xbfb8aa3b, v14
	v_mul_f32_e32 v7, 0xbfb8aa3b, v7
	v_exp_f32_e32 v2, v2
	v_exp_f32_e32 v6, v6
	v_exp_f32_e32 v14, v14
	v_exp_f32_e32 v7, v7
	v_add_f32_e32 v2, 1.0, v2
	v_add_f32_e32 v15, 1.0, v6
	v_add_f32_e32 v14, 1.0, v14
	v_add_f32_e32 v16, 1.0, v7
	v_rcp_f32_e32 v6, v2
	v_rcp_f32_e32 v7, v15
	v_rcp_f32_e32 v14, v14
	v_rcp_f32_e32 v15, v16
	s_waitcnt vmcnt(0)
	v_lshlrev_b32_e32 v16, 16, v8
	v_and_b32_e32 v17, 0xffff0000, v8
	v_lshlrev_b32_e32 v8, 16, v9
	v_and_b32_e32 v9, 0xffff0000, v9
	v_pk_fma_f32 v[8:9], v[12:13], v[14:15], v[8:9]
	v_pk_fma_f32 v[6:7], v[10:11], v[6:7], v[16:17]
	s_nop 0
	v_cvt_pk_bf16_f32 v6, v6, v7
	v_cvt_pk_bf16_f32 v7, v8, v9
	global_store_dwordx2 v[4:5], v[6:7], off
	s_barrier
	s_cbranch_scc0 .LBB0_800

; #define LAS __attribute__((address_space(3)))
; __device__ __forceinline__ unsigned pk2(float lo, float hi) { return pg8::cvt_pk_bf16(lo, hi); }
; __device__ __forceinline__ float bflo(unsigned w) { return __uint_as_float(w << 16); }
; __device__ __forceinline__ float bfhi(unsigned w) { return __uint_as_float(w & 0xffff0000u); }
; __device__ __forceinline__ int crow(int r, int hi) { return (r & 3) + 8 * (r >> 2) + 4 * hi; }
; template <int MODE> __device__ __forceinline__ void small_gemm_res(LAS unsigned char* lds, const bf16* A, const bf16* Bt, int K, const float* base, const bf16* baseb, float* H, bf16* XN, float* SS, float alpha, const bf16* GGs, int bx, int G, int tid) {
;     ...
;         for (int k = 0; k < kw; k += 16) {
;             const bf16x8 x = *(const bf16x8*)(ap + k), w0 = *(const bf16x8*)(b0p + k), w1 = *(const bf16x8*)(b1p + k);
;             acc0 = __builtin_amdgcn_mfma_f32_32x32x16_bf16(w0, x, acc0, 0, 0, 0); acc1 = __builtin_amdgcn_mfma_f32_32x32x16_bf16(w1, x, acc1, 0, 0, 0);
;         }
;         LAS float* Pw = P + w * 2112;
; #pragma unroll
;         for (int r = 0; r < 16; ++r) { Pw[crow(r, hi) * 33 + r32] = acc0[r]; Pw[(32 + crow(r, hi)) * 33 + r32] = acc1[r]; }
;         __syncthreads();
;         const int tok = tid >> 4, nq = tid & 15;
;         float v[4] = {0.f, 0.f, 0.f, 0.f};
; #pragma unroll
;         for (int ww = 0; ww < 8; ++ww)
; #pragma unroll
;             for (int e = 0; e < 4; ++e) v[e] += P[ww * 2112 + (4 * nq + e) * 33 + tok];
;         const size_t off = (size_t)(t0 + tok) * 1024 + n0 + 4 * nq;
;         if (MODE == 0) {
;             f32x4 b; if (baseb) { const u32x2 bw = *(const u32x2*)(baseb + off); b = (f32x4){bflo(bw.x), bfhi(bw.x), bflo(bw.y), bfhi(bw.y)}; } else b = *(const f32x4*)(base + off);
;             const f32x4 hv = (f32x4){b[0] + alpha * v[0], b[1] + alpha * v[1], b[2] + alpha * v[2], b[3] + alpha * v[3]};
;             if (H) *(f32x4*)(H + off) = hv;
;             if (XN) { u32x2 xw; xw.x = pk2(hv[0], hv[1]); xw.y = pk2(hv[2], hv[3]); *(u32x2*)(XN + off) = xw; }
;             if (SS) { float ss = (hv[0] * hv[0] + hv[1] * hv[1]) + (hv[2] * hv[2] + hv[3] * hv[3]);
;                 ss += __shfl_xor(ss, 1); ss += __shfl_xor(ss, 2); ss += __shfl_xor(ss, 4); ss += __shfl_xor(ss, 8);
;                 if (nq == 0) SS[(size_t)(t0 + tok) * 16 + (n0 >> 6)] = ss; }
.LBB0_1009:
	v_lshl_add_u64 v[60:61], v[42:43], 0, s[16:17]
	s_mov_b32 s5, 0x2500000
	v_add_co_u32_e64 v66, s[10:11], s5, v60
	s_mov_b32 s5, 0x2510000
	s_nop 0
	v_addc_co_u32_e64 v67, s[10:11], 0, v61, s[10:11]
	v_add_co_u32_e64 v68, s[10:11], s5, v60
	s_nop 0
	v_addc_co_u32_e64 v69, s[10:11], 0, v61, s[10:11]
	v_lshl_add_u64 v[64:65], v[44:45], 0, s[16:17]
	s_add_i32 s4, s4, 64
	v_lshl_add_u64 v[42:43], v[42:43], 0, s[76:77]
	v_lshl_add_u64 v[44:45], v[44:45], 0, s[76:77]
	s_cmpk_gt_u32 s4, 0x6f
	global_load_dwordx4 v[72:75], v[66:67], off
	global_load_dwordx4 v[76:79], v[68:69], off
	global_load_dwordx4 v[80:83], v[64:65], off offset:-64
	global_load_dwordx4 v[92:95], v[64:65], off offset:-32
	global_load_dwordx4 v[96:99], v[66:67], off offset:32
	global_load_dwordx4 v[100:103], v[68:69], off offset:32
	global_load_dwordx4 v[104:107], v[64:65], off
	global_load_dwordx4 v[108:111], v[66:67], off offset:64
	global_load_dwordx4 v[112:115], v[68:69], off offset:64
	global_load_dwordx4 v[116:119], v[64:65], off offset:32
	global_load_dwordx4 v[120:123], v[66:67], off offset:96
	global_load_dwordx4 v[124:127], v[68:69], off offset:96
	s_waitcnt vmcnt(9)
	v_mfma_f32_32x32x16_bf16 v[4:19], v[72:75], v[80:83], v[4:19]
	v_mfma_f32_32x32x16_bf16 v[20:35], v[76:79], v[80:83], v[20:35]
	s_waitcnt vmcnt(6)
	v_mfma_f32_32x32x16_bf16 v[4:19], v[96:99], v[92:95], v[4:19]
	v_mfma_f32_32x32x16_bf16 v[20:35], v[100:103], v[92:95], v[20:35]
	s_waitcnt vmcnt(3)
	v_mfma_f32_32x32x16_bf16 v[4:19], v[108:111], v[104:107], v[4:19]
	v_mfma_f32_32x32x16_bf16 v[20:35], v[112:115], v[104:107], v[20:35]
	s_waitcnt vmcnt(0)
	v_mfma_f32_32x32x16_bf16 v[4:19], v[120:123], v[116:119], v[4:19]
	v_mfma_f32_32x32x16_bf16 v[20:35], v[124:127], v[116:119], v[20:35]
	s_cbranch_scc0 .LBB0_1009
	v_add_u32_e32 v2, 0x1000, v48
	s_nop 7
	ds_write2_b32 v48, v4, v5 offset1:33
	s_nop 0
	ds_write2_b32 v2, v20, v21 offset0:32 offset1:65
	ds_write2_b32 v48, v6, v7 offset0:66 offset1:99
	ds_write2_b32 v2, v22, v23 offset0:98 offset1:131
	v_add_u32_e32 v2, 0x400, v48
	v_add_u32_e32 v4, 0x1400, v48
	s_lshl_b32 s4, s6, 1
	ds_write2_b32 v2, v8, v9 offset0:8 offset1:41
	ds_write2_b32 v4, v24, v25 offset0:40 offset1:73
	ds_write2_b32 v2, v10, v11 offset0:74 offset1:107
	ds_write2_b32 v4, v26, v27 offset0:106 offset1:139
	v_add_u32_e32 v2, 0x800, v48
	v_add_u32_e32 v4, 0x1800, v48
	s_andn2_b32 s4, s4, 31
	ds_write2_b32 v2, v12, v13 offset0:16 offset1:49
	ds_write2_b32 v4, v28, v29 offset0:48 offset1:81
	ds_write2_b32 v2, v14, v15 offset0:82 offset1:115
	ds_write2_b32 v4, v30, v31 offset0:114 offset1:147
	v_add_u32_e32 v2, 0xc00, v48
	v_add_u32_e32 v4, 0x1c00, v48
	ds_write2_b32 v2, v16, v17 offset0:24 offset1:57
	ds_write2_b32 v4, v32, v33 offset0:56 offset1:89
	ds_write2_b32 v2, v18, v19 offset0:90 offset1:123
	ds_write2_b32 v4, v34, v35 offset0:122 offset1:155
	v_add_u32_e32 v4, s4, v47
	s_lshl_b32 s5, s6, 6
	v_ashrrev_i32_e32 v5, 31, v4
	s_and_b32 s7, s5, 0x3c0
	v_lshlrev_b64 v[6:7], 11, v[4:5]
	v_lshl_add_u64 v[6:7], s[12:13], 0, v[6:7]
	s_lshl_b32 s78, s7, 1
	v_lshl_add_u64 v[6:7], v[6:7], 0, s[78:79]
	v_mov_b32_e32 v41, v3
	v_lshl_add_u64 v[8:9], v[6:7], 0, v[40:41]
	s_waitcnt lgkmcnt(0)
	s_barrier
	global_load_dwordx2 v[6:7], v[8:9], off
	v_add_u32_e32 v20, 0x4000, v50
	v_add_u32_e32 v22, 0x6000, v50
	v_add_u32_e32 v24, 0x6400, v50
	v_add_u32_e32 v28, 0x8400, v50
	v_add_u32_e32 v32, 0xa400, v50
	v_add_u32_e32 v44, 0xe400, v50
	v_add_u32_e32 v2, 0x2000, v50
	v_add_u32_e32 v41, 0xc400, v50
	v_add_u32_e32 v51, 0xe800, v50
	ds_read2_b32 v[10:11], v50 offset1:33
	ds_read2_b32 v[12:13], v50 offset0:66 offset1:99
	ds_read2_b32 v[14:15], v2 offset0:64 offset1:97
	ds_read2_b32 v[16:17], v2 offset0:130 offset1:163
	ds_read2_b32 v[18:19], v20 offset0:128 offset1:161
	ds_read2_b32 v[20:21], v20 offset0:194 offset1:227
	ds_read2_b32 v[22:23], v22 offset0:192 offset1:225
	ds_read2_b32 v[24:25], v24 offset0:2 offset1:35
	ds_read2_b32 v[26:27], v28 offset1:33
	ds_read2_b32 v[28:29], v28 offset0:66 offset1:99
	ds_read2_b32 v[30:31], v32 offset0:64 offset1:97
	ds_read2_b32 v[32:33], v32 offset0:130 offset1:163
	ds_read2_b32 v[34:35], v41 offset0:128 offset1:161
	ds_read2_b32 v[42:43], v41 offset0:194 offset1:227
	ds_read2_b32 v[44:45], v44 offset0:192 offset1:225
	ds_read2_b32 v[52:53], v51 offset0:2 offset1:35
	s_waitcnt lgkmcnt(14)
	v_pk_add_f32 v[10:11], v[10:11], 0 op_sel_hi:[1,0]
	v_pk_add_f32 v[12:13], v[12:13], 0 op_sel_hi:[1,0]
	s_waitcnt lgkmcnt(13)
	v_pk_add_f32 v[10:11], v[10:11], v[14:15]
	s_waitcnt lgkmcnt(12)
	v_pk_add_f32 v[12:13], v[12:13], v[16:17]
	s_waitcnt lgkmcnt(11)
	v_pk_add_f32 v[10:11], v[10:11], v[18:19]
	s_waitcnt lgkmcnt(10)
	v_pk_add_f32 v[12:13], v[12:13], v[20:21]
	s_waitcnt lgkmcnt(9)
	v_pk_add_f32 v[10:11], v[10:11], v[22:23]
	s_waitcnt lgkmcnt(8)
	v_pk_add_f32 v[12:13], v[12:13], v[24:25]
	s_waitcnt lgkmcnt(7)
	v_pk_add_f32 v[10:11], v[10:11], v[26:27]
	s_waitcnt lgkmcnt(6)
	v_pk_add_f32 v[12:13], v[12:13], v[28:29]
	s_waitcnt lgkmcnt(5)
	v_pk_add_f32 v[10:11], v[10:11], v[30:31]
	s_waitcnt lgkmcnt(4)
	v_pk_add_f32 v[12:13], v[12:13], v[32:33]
	s_waitcnt lgkmcnt(3)
	v_pk_add_f32 v[10:11], v[10:11], v[34:35]
	s_waitcnt lgkmcnt(2)
	v_pk_add_f32 v[12:13], v[12:13], v[42:43]
	s_waitcnt lgkmcnt(1)
	v_pk_add_f32 v[10:11], v[10:11], v[44:45]
	s_waitcnt lgkmcnt(0)
	v_pk_add_f32 v[12:13], v[12:13], v[52:53]
	s_waitcnt vmcnt(0)
	v_lshlrev_b32_e32 v14, 16, v6
	v_and_b32_e32 v15, 0xffff0000, v6
	v_lshlrev_b32_e32 v6, 16, v7
	v_and_b32_e32 v7, 0xffff0000, v7
	v_pk_add_f32 v[10:11], v[10:11], v[14:15]
	v_pk_add_f32 v[12:13], v[12:13], v[6:7]
	v_pk_mul_f32 v[6:7], v[10:11], v[10:11]
	v_pk_mul_f32 v[14:15], v[12:13], v[12:13]
	v_add_f32_e32 v6, v6, v7
	v_add_f32_e32 v2, v14, v15
	v_add_f32_e32 v2, v6, v2
	ds_bpermute_b32 v6, v181, v2
	v_cvt_pk_bf16_f32 v10, v10, v11
	v_cvt_pk_bf16_f32 v11, v12, v13
	global_store_dwordx2 v[8:9], v[10:11], off
	s_waitcnt lgkmcnt(0)
	v_add_f32_e32 v2, v2, v6
	ds_bpermute_b32 v6, v196, v2
	s_waitcnt lgkmcnt(0)
	v_add_f32_e32 v2, v2, v6
	ds_bpermute_b32 v6, v197, v2
	s_waitcnt lgkmcnt(0)
	v_add_f32_e32 v2, v2, v6
	ds_bpermute_b32 v6, v198, v2
	s_and_saveexec_b64 s[4:5], vcc
	s_cbranch_execz .LBB0_1007
	v_lshlrev_b64 v[4:5], 6, v[4:5]
	v_lshl_add_u64 v[4:5], s[14:15], 0, v[4:5]
	s_lshr_b32 s78, s7, 4
	s_waitcnt lgkmcnt(0)
	v_add_f32_e32 v2, v2, v6
	v_lshl_add_u64 v[4:5], v[4:5], 0, s[78:79]
	global_store_dword v[4:5], v2, off
	s_branch .LBB0_1007

; template <int MODE> __device__ __forceinline__ void small_gemm_res(LAS unsigned char* lds, const bf16* A, const bf16* Bt, int K, const float* base, const bf16* baseb, float* H, bf16* XN, float* SS, float alpha, const bf16* GGs, int bx, int G, int tid) {
;     ...
;     for (int tile = bx; tile < 256; tile += G) {
;         const int t0 = (tile >> 4) * 32, n0 = (tile & 15) * 64;
;         f32x16 acc0, acc1;
; #pragma unroll
;         for (int r = 0; r < 16; ++r) { acc0[r] = 0.f; acc1[r] = 0.f; }
;         const bf16* ap = A + (size_t)(t0 + r32) * K + w * kw + 8 * hi;
;         const bf16* b0p = Bt + (size_t)(n0 + r32) * K + w * kw + 8 * hi; const bf16* b1p = b0p + (size_t)32 * K;
; #pragma unroll 4
;         for (int k = 0; k < kw; k += 16) {
;             const bf16x8 x = *(const bf16x8*)(ap + k), w0 = *(const bf16x8*)(b0p + k), w1 = *(const bf16x8*)(b1p + k);
;             acc0 = __builtin_amdgcn_mfma_f32_32x32x16_bf16(w0, x, acc0, 0, 0, 0); acc1 = __builtin_amdgcn_mfma_f32_32x32x16_bf16(w1, x, acc1, 0, 0, 0);
;         }
.LBB0_1179:
	s_and_b32 s2, s13, 0xffffffe0
	s_and_b32 s1, s3, 0x3c0
	v_or_b32_e32 v0, s2, v40
	v_or_b32_e32 v1, s1, v40
	v_mad_i64_i32 v[84:85], s[10:11], v0, s0, v[34:35]
	v_mul_u32_u24_e32 v0, 0xb00, v1
	v_lshlrev_b32_e32 v32, 1, v0
	v_lshl_add_u64 v[86:87], v[36:37], 0, v[32:33]
	v_add_co_u32_e32 v88, vcc, 0x2c000, v86
	s_lshl_b32 s8, s1, 1
	v_addc_co_u32_e32 v89, vcc, 0, v87, vcc
	s_add_i32 s56, s56, s70
	s_add_i32 s3, s3, s12
	s_add_i32 s13, s13, s14
	s_cmpk_lt_i32 s56, 0x100
	v_add_u32_e32 v60, s2, v41
	v_ashrrev_i32_e32 v61, 31, v60
	v_lshlrev_b64 v[60:61], 11, v[60:61]
	v_lshl_add_u64 v[60:61], s[6:7], 0, v[60:61]
	v_lshl_add_u64 v[60:61], v[60:61], 0, s[8:9]
	v_lshl_add_u64 v[60:61], v[60:61], 0, v[38:39]
	global_load_dwordx4 v[64:67], v[86:87], off
	global_load_dwordx4 v[68:71], v[84:85], off
	global_load_dwordx4 v[72:75], v[88:89], off
	global_load_dwordx4 v[76:79], v[86:87], off offset:32
	global_load_dwordx4 v[80:83], v[84:85], off offset:32
	global_load_dwordx4 v[92:95], v[88:89], off offset:32
	global_load_dwordx4 v[96:99], v[86:87], off offset:64
	global_load_dwordx4 v[100:103], v[84:85], off offset:64
	global_load_dwordx4 v[104:107], v[88:89], off offset:64
	global_load_dwordx4 v[108:111], v[86:87], off offset:96
	global_load_dwordx4 v[112:115], v[84:85], off offset:96
	global_load_dwordx4 v[116:119], v[88:89], off offset:96
	global_load_dwordx4 v[120:123], v[86:87], off offset:128
	global_load_dwordx4 v[124:127], v[84:85], off offset:128
	global_load_dwordx4 v[208:211], v[88:89], off offset:128
	global_load_dwordx4 v[212:215], v[86:87], off offset:160
	global_load_dwordx4 v[216:219], v[84:85], off offset:160
	global_load_dwordx4 v[220:223], v[88:89], off offset:160
	global_load_dwordx4 v[224:227], v[86:87], off offset:192
	global_load_dwordx4 v[228:231], v[84:85], off offset:192
	global_load_dwordx4 v[232:235], v[88:89], off offset:192
	global_load_dwordx4 v[236:239], v[86:87], off offset:224
	global_load_dwordx4 v[166:169], v[84:85], off offset:224
	global_load_dwordx4 v[170:173], v[88:89], off offset:224
	global_load_dwordx4 v[174:177], v[86:87], off offset:256
	global_load_dwordx4 v[182:185], v[84:85], off offset:256
	global_load_dwordx4 v[186:189], v[88:89], off offset:256
	s_waitcnt vmcnt(24)
	v_mfma_f32_32x32x16_bf16 v[16:31], v[64:67], v[68:71], 0
	v_mfma_f32_32x32x16_bf16 v[0:15], v[72:75], v[68:71], 0
	global_load_dwordx4 v[64:67], v[86:87], off offset:288
	global_load_dwordx4 v[68:71], v[84:85], off offset:288
	global_load_dwordx4 v[72:75], v[88:89], off offset:288
	s_waitcnt vmcnt(24)
	v_mfma_f32_32x32x16_bf16 v[16:31], v[76:79], v[80:83], v[16:31]
	v_mfma_f32_32x32x16_bf16 v[0:15], v[92:95], v[80:83], v[0:15]
	global_load_dwordx4 v[76:79], v[86:87], off offset:320
	global_load_dwordx4 v[80:83], v[84:85], off offset:320
	global_load_dwordx4 v[92:95], v[88:89], off offset:320
	s_waitcnt vmcnt(24)
	v_mfma_f32_32x32x16_bf16 v[16:31], v[96:99], v[100:103], v[16:31]
	v_mfma_f32_32x32x16_bf16 v[0:15], v[104:107], v[100:103], v[0:15]
	global_load_dwordx4 v[96:99], v[86:87], off offset:352
	global_load_dwordx4 v[100:103], v[84:85], off offset:352
	global_load_dwordx4 v[104:107], v[88:89], off offset:352
	s_waitcnt vmcnt(24)
	v_mfma_f32_32x32x16_bf16 v[16:31], v[108:111], v[112:115], v[16:31]
	v_mfma_f32_32x32x16_bf16 v[0:15], v[116:119], v[112:115], v[0:15]
	global_load_dwordx4 v[108:111], v[86:87], off offset:384
	global_load_dwordx4 v[112:115], v[84:85], off offset:384
	global_load_dwordx4 v[116:119], v[88:89], off offset:384
	s_waitcnt vmcnt(24)
	v_mfma_f32_32x32x16_bf16 v[16:31], v[120:123], v[124:127], v[16:31]
	v_mfma_f32_32x32x16_bf16 v[0:15], v[208:211], v[124:127], v[0:15]
	global_load_dwordx4 v[120:123], v[86:87], off offset:416
	global_load_dwordx4 v[124:127], v[84:85], off offset:416
	global_load_dwordx4 v[208:211], v[88:89], off offset:416
	s_waitcnt vmcnt(24)
	v_mfma_f32_32x32x16_bf16 v[16:31], v[212:215], v[216:219], v[16:31]
	v_mfma_f32_32x32x16_bf16 v[0:15], v[220:223], v[216:219], v[0:15]
	global_load_dwordx4 v[212:215], v[86:87], off offset:448
	global_load_dwordx4 v[216:219], v[84:85], off offset:448
	global_load_dwordx4 v[220:223], v[88:89], off offset:448
	s_waitcnt vmcnt(24)
	v_mfma_f32_32x32x16_bf16 v[16:31], v[224:227], v[228:231], v[16:31]
	v_mfma_f32_32x32x16_bf16 v[0:15], v[232:235], v[228:231], v[0:15]
	global_load_dwordx4 v[224:227], v[86:87], off offset:480
	global_load_dwordx4 v[228:231], v[84:85], off offset:480
	global_load_dwordx4 v[232:235], v[88:89], off offset:480
	s_waitcnt vmcnt(24)
	v_mfma_f32_32x32x16_bf16 v[16:31], v[236:239], v[166:169], v[16:31]
	v_mfma_f32_32x32x16_bf16 v[0:15], v[170:173], v[166:169], v[0:15]
	global_load_dwordx4 v[236:239], v[86:87], off offset:512
	global_load_dwordx4 v[166:169], v[84:85], off offset:512
	global_load_dwordx4 v[170:173], v[88:89], off offset:512
	s_waitcnt vmcnt(24)
	v_mfma_f32_32x32x16_bf16 v[16:31], v[174:177], v[182:185], v[16:31]
	v_mfma_f32_32x32x16_bf16 v[0:15], v[186:189], v[182:185], v[0:15]
	global_load_dwordx4 v[174:177], v[86:87], off offset:544
	global_load_dwordx4 v[182:185], v[84:85], off offset:544
	global_load_dwordx4 v[186:189], v[88:89], off offset:544
	s_waitcnt vmcnt(24)
	v_mfma_f32_32x32x16_bf16 v[16:31], v[64:67], v[68:71], v[16:31]
	v_mfma_f32_32x32x16_bf16 v[0:15], v[72:75], v[68:71], v[0:15]
	global_load_dwordx4 v[64:67], v[86:87], off offset:576
	global_load_dwordx4 v[68:71], v[84:85], off offset:576
	global_load_dwordx4 v[72:75], v[88:89], off offset:576
	s_waitcnt vmcnt(24)
; #define LAS __attribute__((address_space(3)))
; __device__ __forceinline__ unsigned pk2(float lo, float hi) { return pg8::cvt_pk_bf16(lo, hi); }
; __device__ __forceinline__ float bflo(unsigned w) { return __uint_as_float(w << 16); }
; __device__ __forceinline__ float bfhi(unsigned w) { return __uint_as_float(w & 0xffff0000u); }
; __device__ __forceinline__ int crow(int r, int hi) { return (r & 3) + 8 * (r >> 2) + 4 * hi; }
; template <int MODE> __device__ __forceinline__ void small_gemm_res(LAS unsigned char* lds, const bf16* A, const bf16* Bt, int K, const float* base, const bf16* baseb, float* H, bf16* XN, float* SS, float alpha, const bf16* GGs, int bx, int G, int tid) {
;     ...
;         for (int k = 0; k < kw; k += 16) {
;             const bf16x8 x = *(const bf16x8*)(ap + k), w0 = *(const bf16x8*)(b0p + k), w1 = *(const bf16x8*)(b1p + k);
;             acc0 = __builtin_amdgcn_mfma_f32_32x32x16_bf16(w0, x, acc0, 0, 0, 0); acc1 = __builtin_amdgcn_mfma_f32_32x32x16_bf16(w1, x, acc1, 0, 0, 0);
;         }
;         LAS float* Pw = P + w * 2112;
; #pragma unroll
;         for (int r = 0; r < 16; ++r) { Pw[crow(r, hi) * 33 + r32] = acc0[r]; Pw[(32 + crow(r, hi)) * 33 + r32] = acc1[r]; }
;         __syncthreads();
;         const int tok = tid >> 4, nq = tid & 15;
;         float v[4] = {0.f, 0.f, 0.f, 0.f};
; #pragma unroll
;         for (int ww = 0; ww < 8; ++ww)
; #pragma unroll
;             for (int e = 0; e < 4; ++e) v[e] += P[ww * 2112 + (4 * nq + e) * 33 + tok];
;         const size_t off = (size_t)(t0 + tok) * 1024 + n0 + 4 * nq;
;         if (MODE == 0) {
;             f32x4 b; if (baseb) { const u32x2 bw = *(const u32x2*)(baseb + off); b = (f32x4){bflo(bw.x), bfhi(bw.x), bflo(bw.y), bfhi(bw.y)}; } else b = *(const f32x4*)(base + off);
;             const f32x4 hv = (f32x4){b[0] + alpha * v[0], b[1] + alpha * v[1], b[2] + alpha * v[2], b[3] + alpha * v[3]};
;             if (H) *(f32x4*)(H + off) = hv;
;             if (XN) { u32x2 xw; xw.x = pk2(hv[0], hv[1]); xw.y = pk2(hv[2], hv[3]); *(u32x2*)(XN + off) = xw; }
	v_mfma_f32_32x32x16_bf16 v[16:31], v[76:79], v[80:83], v[16:31]
	v_mfma_f32_32x32x16_bf16 v[0:15], v[92:95], v[80:83], v[0:15]
	global_load_dwordx4 v[76:79], v[86:87], off offset:608
	global_load_dwordx4 v[80:83], v[84:85], off offset:608
	global_load_dwordx4 v[92:95], v[88:89], off offset:608
	s_waitcnt vmcnt(24)
	v_mfma_f32_32x32x16_bf16 v[16:31], v[96:99], v[100:103], v[16:31]
	v_mfma_f32_32x32x16_bf16 v[0:15], v[104:107], v[100:103], v[0:15]
	global_load_dwordx4 v[96:99], v[86:87], off offset:640
	global_load_dwordx4 v[100:103], v[84:85], off offset:640
	global_load_dwordx4 v[104:107], v[88:89], off offset:640
	s_waitcnt vmcnt(24)
	v_mfma_f32_32x32x16_bf16 v[16:31], v[108:111], v[112:115], v[16:31]
	v_mfma_f32_32x32x16_bf16 v[0:15], v[116:119], v[112:115], v[0:15]
	global_load_dwordx4 v[108:111], v[86:87], off offset:672
	global_load_dwordx4 v[112:115], v[84:85], off offset:672
	global_load_dwordx4 v[116:119], v[88:89], off offset:672
	s_waitcnt vmcnt(24)
	v_mfma_f32_32x32x16_bf16 v[16:31], v[120:123], v[124:127], v[16:31]
	v_mfma_f32_32x32x16_bf16 v[0:15], v[208:211], v[124:127], v[0:15]
	s_waitcnt vmcnt(21)
	v_mfma_f32_32x32x16_bf16 v[16:31], v[212:215], v[216:219], v[16:31]
	v_mfma_f32_32x32x16_bf16 v[0:15], v[220:223], v[216:219], v[0:15]
	s_waitcnt vmcnt(18)
	v_mfma_f32_32x32x16_bf16 v[16:31], v[224:227], v[228:231], v[16:31]
	v_mfma_f32_32x32x16_bf16 v[0:15], v[232:235], v[228:231], v[0:15]
	s_waitcnt vmcnt(15)
	v_mfma_f32_32x32x16_bf16 v[16:31], v[236:239], v[166:169], v[16:31]
	v_mfma_f32_32x32x16_bf16 v[0:15], v[170:173], v[166:169], v[0:15]
	s_waitcnt vmcnt(12)
	v_mfma_f32_32x32x16_bf16 v[16:31], v[174:177], v[182:185], v[16:31]
	v_mfma_f32_32x32x16_bf16 v[0:15], v[186:189], v[182:185], v[0:15]
	s_waitcnt vmcnt(9)
	v_mfma_f32_32x32x16_bf16 v[16:31], v[64:67], v[68:71], v[16:31]
	v_mfma_f32_32x32x16_bf16 v[0:15], v[72:75], v[68:71], v[0:15]
	s_waitcnt vmcnt(6)
	v_mfma_f32_32x32x16_bf16 v[16:31], v[76:79], v[80:83], v[16:31]
	v_mfma_f32_32x32x16_bf16 v[0:15], v[92:95], v[80:83], v[0:15]
	s_waitcnt vmcnt(3)
	v_mfma_f32_32x32x16_bf16 v[16:31], v[96:99], v[100:103], v[16:31]
	v_mfma_f32_32x32x16_bf16 v[0:15], v[104:107], v[100:103], v[0:15]
	s_waitcnt vmcnt(0)
	v_mfma_f32_32x32x16_bf16 v[16:31], v[108:111], v[112:115], v[16:31]
	v_mfma_f32_32x32x16_bf16 v[0:15], v[116:119], v[112:115], v[0:15]
	s_nop 9
	ds_write2_b32 v42, v16, v17 offset1:33
	ds_write2_b32 v42, v18, v19 offset0:66 offset1:99
	ds_write2_b32 v45, v20, v21 offset0:8 offset1:41
	ds_write2_b32 v45, v22, v23 offset0:74 offset1:107
	ds_write2_b32 v47, v24, v25 offset0:16 offset1:49
	ds_write2_b32 v47, v26, v27 offset0:82 offset1:115
	ds_write2_b32 v49, v28, v29 offset0:24 offset1:57
	ds_write2_b32 v49, v30, v31 offset0:90 offset1:123
	ds_write2_b32 v44, v0, v1 offset0:32 offset1:65
	ds_write2_b32 v44, v2, v3 offset0:98 offset1:131
	ds_write2_b32 v46, v4, v5 offset0:40 offset1:73
	ds_write2_b32 v46, v6, v7 offset0:106 offset1:139
	ds_write2_b32 v48, v8, v9 offset0:48 offset1:81
	ds_write2_b32 v48, v10, v11 offset0:114 offset1:147
	ds_write2_b32 v50, v12, v13 offset0:56 offset1:89
	ds_write2_b32 v50, v14, v15 offset0:122 offset1:155
	s_waitcnt lgkmcnt(0)
	s_barrier
	global_load_dwordx2 v[0:1], v[60:61], off
	ds_read2_b32 v[2:3], v43 offset1:33
	ds_read2_b32 v[4:5], v43 offset0:66 offset1:99
	ds_read2_b32 v[6:7], v51 offset0:64 offset1:97
	ds_read2_b32 v[8:9], v51 offset0:130 offset1:163
	ds_read2_b32 v[10:11], v52 offset0:128 offset1:161
	ds_read2_b32 v[12:13], v52 offset0:194 offset1:227
	ds_read2_b32 v[14:15], v53 offset0:192 offset1:225
	ds_read2_b32 v[16:17], v54 offset0:2 offset1:35
	ds_read2_b32 v[18:19], v55 offset1:33
	ds_read2_b32 v[20:21], v55 offset0:66 offset1:99
	ds_read2_b32 v[22:23], v56 offset0:64 offset1:97
	ds_read2_b32 v[24:25], v56 offset0:130 offset1:163
	ds_read2_b32 v[26:27], v57 offset0:128 offset1:161
	ds_read2_b32 v[28:29], v57 offset0:194 offset1:227
	ds_read2_b32 v[30:31], v58 offset0:192 offset1:225
	ds_read2_b32 v[62:63], v59 offset0:2 offset1:35
	s_waitcnt lgkmcnt(14)
	v_pk_add_f32 v[2:3], v[2:3], 0 op_sel_hi:[1,0]
	v_pk_add_f32 v[4:5], v[4:5], 0 op_sel_hi:[1,0]
	s_waitcnt lgkmcnt(13)
	v_pk_add_f32 v[2:3], v[2:3], v[6:7]
	s_waitcnt lgkmcnt(12)
	v_pk_add_f32 v[4:5], v[4:5], v[8:9]
	s_waitcnt lgkmcnt(11)
	v_pk_add_f32 v[2:3], v[2:3], v[10:11]
	s_waitcnt lgkmcnt(10)
	v_pk_add_f32 v[4:5], v[4:5], v[12:13]
	s_waitcnt lgkmcnt(9)
	v_pk_add_f32 v[2:3], v[2:3], v[14:15]
	s_waitcnt lgkmcnt(8)
	v_pk_add_f32 v[4:5], v[4:5], v[16:17]
	s_waitcnt lgkmcnt(7)
	v_pk_add_f32 v[2:3], v[2:3], v[18:19]
	s_waitcnt lgkmcnt(6)
	v_pk_add_f32 v[4:5], v[4:5], v[20:21]
	s_waitcnt lgkmcnt(5)
	v_pk_add_f32 v[2:3], v[2:3], v[22:23]
	s_waitcnt lgkmcnt(4)
	v_pk_add_f32 v[4:5], v[4:5], v[24:25]
	s_waitcnt lgkmcnt(3)
	v_pk_add_f32 v[2:3], v[2:3], v[26:27]
	s_waitcnt lgkmcnt(2)
	v_pk_add_f32 v[4:5], v[4:5], v[28:29]
	s_waitcnt lgkmcnt(1)
	v_pk_add_f32 v[2:3], v[2:3], v[30:31]
	s_waitcnt lgkmcnt(0)
	v_pk_add_f32 v[4:5], v[4:5], v[62:63]
	s_waitcnt vmcnt(0)
	v_lshlrev_b32_e32 v6, 16, v0
	v_and_b32_e32 v7, 0xffff0000, v0
	v_lshlrev_b32_e32 v0, 16, v1
	v_and_b32_e32 v1, 0xffff0000, v1
	v_pk_fma_f32 v[2:3], v[2:3], 0.5, v[6:7] op_sel_hi:[1,0,1]
	v_pk_fma_f32 v[0:1], v[4:5], 0.5, v[0:1] op_sel_hi:[1,0,1]
	v_cvt_pk_bf16_f32 v2, v2, v3
	v_cvt_pk_bf16_f32 v3, v0, v1
	global_store_dwordx2 v[60:61], v[2:3], off
	s_barrier
	s_cbranch_scc1 .LBB0_1179
